# attention loop: first two V fragments of each PV segment requested from inside the preceding QK segment (fewer LDS reads queued at segment heads)
# baseline (speedup 1.0000x reference)
; #define LAS __attribute__((address_space(3)))
; template <bool SHIFT> DI void attn_unit(LAS unsigned char* lds, const bf16_t* Qb, const bf16_t* Kb, const bf16_t* Vt, bf16_t* concat,
;                   int b, int h, int qt, float shift2, float lam, int lam_init_bits, const float* subln_g) {
;     ...
;     for (int kt = 0; kt < nkt; ++kt) {
;         const int cur = kt & 1, nx = cur ^ 1;
;         const int vnx = vcur == 2 ? 0 : vcur + 1;
;         const bool pf = (kt + 1 < nkt);
;         const size_t ko = (size_t)(kt + 1) * 64;
;         if (pf) { *(LAS u32x4*)(lds + K_OFF + nx * K_BYTES + krow0 * QP + kc * 16) = sg0; *(LAS u32x4*)(lds + K_OFF + nx * K_BYTES + (krow0 + 32) * QP + kc * 16) = sg1;
;             sg0 = *(const u32x4*)(vg + (size_t)(vrow0) * TPB + ko + vc * 8); sg1 = *(const u32x4*)(vg + (size_t)(vrow0 + 64) * TPB + ko + vc * 8); }
;         const LAS unsigned char* kb = lds + K_OFF + cur * K_BYTES + r * QP + hh * 16;
;         const LAS unsigned char* vb = lds + V_OFF + vcur * V_BYTES + r * VP + hh * 16;
; #pragma unroll
;         for (int half = 0; half < 2; ++half) {
;             if (lag) PVH(Pc, vold);
;             QKEXP(Pc, half);
;             if (half == 0 && pf) { *(LAS u32x4*)(lds + V_OFF + vnx * V_BYTES + vrow0 * VP + vc * 16) = sg0; *(LAS u32x4*)(lds + V_OFF + vnx * V_BYTES + (vrow0 + 64) * VP + vc * 16) = sg1;
;                 if (kt + 2 < nkt) { sg0 = *(const u32x4*)(kg + (ko + 64 + krow0) * 1024 + kc * 8); sg1 = *(const u32x4*)(kg + (ko + 64 + krow0 + 32) * 1024 + kc * 8); } }
.Lattn_loop:
	s_mul_i32 vcc_lo, s40, 0x4800
	v_add_u32_e32 v217, vcc_lo, v213
	ds_read_b128 v[178:181], v254
	ds_read_b128 v[186:189], v211
	ds_read_b128 v[182:185], v254 offset:32
	ds_read_b128 v[190:193], v211 offset:32
	s_add_i32 vcc_lo, s40, 1
	s_cmp_lg_u32 s40, 2
	s_cselect_b32 s65, vcc_lo, 0
	s_mul_i32 s37, s65, 0x4800
	s_waitcnt vmcnt(0)
	ds_write_b128 v137, v[144:147]
	ds_write_b128 v142, v[148:151]
	global_load_dwordx4 v[144:147], v[138:139], off
	global_load_dwordx4 v[148:151], v[168:169], off
	s_waitcnt lgkmcnt(4)
	v_mfma_f32_32x32x16_bf16 v[238:253], v[178:181], v[186:189], 0
	ds_read_b128 v[178:181], v254 offset:64
	ds_read_b128 v[186:189], v211 offset:64
	s_waitcnt lgkmcnt(4)
	v_mfma_f32_32x32x16_bf16 v[238:253], v[182:185], v[190:193], v[238:253]
	ds_read_b128 v[182:185], v254 offset:96
	ds_read_b128 v[190:193], v211 offset:96
	s_waitcnt lgkmcnt(2)
	v_mfma_f32_32x32x16_bf16 v[238:253], v[178:181], v[186:189], v[238:253]
	ds_read_b128 v[228:231], v136
	ds_read_b128 v[178:181], v254 offset:128
	ds_read_b128 v[186:189], v211 offset:128
	s_waitcnt lgkmcnt(3)
	v_mfma_f32_32x32x16_bf16 v[238:253], v[182:185], v[190:193], v[238:253]
	ds_read_b128 v[232:235], v136 offset:4608
	ds_read_b128 v[182:185], v254 offset:160
	ds_read_b128 v[190:193], v211 offset:160
	s_waitcnt lgkmcnt(5)
	v_mfma_f32_32x32x16_bf16 v[112:127], v[228:231], v[156:159], v[112:127]
	v_mfma_f32_32x32x16_bf16 v[96:111], v[228:231], v[132:135], v[96:111]
	ds_read_b128 v[228:231], v136 offset:9216
	s_nop 7
	s_waitcnt lgkmcnt(3)
	v_mfma_f32_32x32x16_bf16 v[80:95], v[232:235], v[156:159], v[80:95]
	v_exp_f32_e32 v238, v238
	v_exp_f32_e32 v239, v239
	v_exp_f32_e32 v240, v240
	v_exp_f32_e32 v241, v241
	v_add_f32_e32 v174, v238, v239
	v_add_f32_e32 v175, v240, v241
	v_cvt_pk_bf16_f32 v194, v238, v239
	v_mfma_f32_32x32x16_bf16 v[64:79], v[232:235], v[132:135], v[64:79]
	ds_read_b128 v[232:235], v136 offset:13824
	v_cvt_pk_bf16_f32 v195, v240, v241
	v_exp_f32_e32 v242, v242
	v_exp_f32_e32 v243, v243
	v_exp_f32_e32 v244, v244
	v_exp_f32_e32 v245, v245
	v_add_f32_e32 v174, v174, v242
	v_add_f32_e32 v175, v175, v243
	s_waitcnt lgkmcnt(1)
	v_mfma_f32_32x32x16_bf16 v[32:47], v[228:231], v[156:159], v[32:47]
	v_add_f32_e32 v174, v174, v244
	v_add_f32_e32 v175, v175, v245
	v_cvt_pk_bf16_f32 v196, v242, v243
	v_cvt_pk_bf16_f32 v197, v244, v245
	v_exp_f32_e32 v246, v246
	v_exp_f32_e32 v247, v247
	v_exp_f32_e32 v248, v248
	v_mfma_f32_32x32x16_bf16 v[48:63], v[228:231], v[132:135], v[48:63]
	ds_read_b128 v[228:231], v136 offset:32
	v_exp_f32_e32 v249, v249
	v_add_f32_e32 v174, v174, v246
	v_add_f32_e32 v175, v175, v247
	v_add_f32_e32 v174, v174, v248
	v_add_f32_e32 v175, v175, v249
	v_cvt_pk_bf16_f32 v198, v246, v247
	v_cvt_pk_bf16_f32 v199, v248, v249
	s_waitcnt lgkmcnt(1)
	v_mfma_f32_32x32x16_bf16 v[16:31], v[232:235], v[156:159], v[16:31]
	v_exp_f32_e32 v250, v250
	v_exp_f32_e32 v251, v251
	v_exp_f32_e32 v252, v252
	v_exp_f32_e32 v253, v253
	v_add_f32_e32 v174, v174, v250
	v_add_f32_e32 v175, v175, v251
	v_mfma_f32_32x32x16_bf16 v[0:15], v[232:235], v[132:135], v[0:15]
	ds_read_b128 v[232:235], v136 offset:4640
	v_add_f32_e32 v174, v174, v252
	v_add_f32_e32 v175, v175, v253
	v_cvt_pk_bf16_f32 v200, v250, v251
	v_cvt_pk_bf16_f32 v201, v252, v253
	v_add_f32_e32 v174, v174, v175
	v_add_f32_e32 v165, v165, v174
	v_mfma_f32_32x32x16_bf16 v[238:253], v[178:181], v[186:189], 0
	ds_read_b128 v[178:181], v254 offset:192
	ds_read_b128 v[186:189], v211 offset:192
	v_mfma_f32_32x32x16_bf16 v[238:253], v[182:185], v[190:193], v[238:253]
	ds_read_b128 v[182:185], v254 offset:224
	ds_read_b128 v[190:193], v211 offset:224
	s_waitcnt lgkmcnt(2)
	v_mfma_f32_32x32x16_bf16 v[238:253], v[178:181], v[186:189], v[238:253]
	ds_read_b128 v[178:181], v254 offset:8704
	ds_read_b128 v[186:189], v211
	s_waitcnt lgkmcnt(2)
	v_mfma_f32_32x32x16_bf16 v[238:253], v[182:185], v[190:193], v[238:253]
	ds_read_b128 v[182:185], v254 offset:8736
	ds_read_b128 v[190:193], v211 offset:32
	v_mfma_f32_32x32x16_bf16 v[112:127], v[228:231], v[152:155], v[112:127]
	v_mfma_f32_32x32x16_bf16 v[96:111], v[228:231], v[128:131], v[96:111]
	ds_read_b128 v[228:231], v136 offset:9248
	s_nop 7
	v_mfma_f32_32x32x16_bf16 v[80:95], v[232:235], v[152:155], v[80:95]
	v_exp_f32_e32 v238, v238
	v_exp_f32_e32 v239, v239
	v_exp_f32_e32 v240, v240
	v_exp_f32_e32 v241, v241
	v_add_f32_e32 v174, v238, v239
	v_add_f32_e32 v175, v240, v241
	v_cvt_pk_bf16_f32 v202, v238, v239
	v_mfma_f32_32x32x16_bf16 v[64:79], v[232:235], v[128:131], v[64:79]
	ds_read_b128 v[232:235], v136 offset:13856
	v_cvt_pk_bf16_f32 v203, v240, v241
	v_exp_f32_e32 v242, v242
	v_exp_f32_e32 v243, v243
	v_exp_f32_e32 v244, v244
	v_exp_f32_e32 v245, v245
	v_add_f32_e32 v174, v174, v242
	v_add_f32_e32 v175, v175, v243
	s_waitcnt lgkmcnt(1)
	v_mfma_f32_32x32x16_bf16 v[32:47], v[228:231], v[152:155], v[32:47]
	v_add_f32_e32 v174, v174, v244
	v_add_f32_e32 v175, v175, v245
	v_cvt_pk_bf16_f32 v204, v242, v243
	v_cvt_pk_bf16_f32 v205, v244, v245
	v_exp_f32_e32 v246, v246
	v_exp_f32_e32 v247, v247
	v_exp_f32_e32 v248, v248
	v_mfma_f32_32x32x16_bf16 v[48:63], v[228:231], v[128:131], v[48:63]
	v_exp_f32_e32 v249, v249
	v_add_f32_e32 v174, v174, v246
	v_add_f32_e32 v175, v175, v247
	v_add_f32_e32 v174, v174, v248
	v_add_f32_e32 v175, v175, v249
	v_cvt_pk_bf16_f32 v206, v246, v247
	v_cvt_pk_bf16_f32 v207, v248, v249
	s_waitcnt lgkmcnt(0)
	v_mfma_f32_32x32x16_bf16 v[16:31], v[232:235], v[152:155], v[16:31]
	v_exp_f32_e32 v250, v250
	v_exp_f32_e32 v251, v251
	v_exp_f32_e32 v252, v252
	v_exp_f32_e32 v253, v253
	v_add_f32_e32 v174, v174, v250
	v_add_f32_e32 v175, v175, v251
	v_mfma_f32_32x32x16_bf16 v[0:15], v[232:235], v[128:131], v[0:15]
	v_add_f32_e32 v174, v174, v252
	v_add_f32_e32 v175, v175, v253
	v_cvt_pk_bf16_f32 v208, v250, v251
	v_cvt_pk_bf16_f32 v209, v252, v253
	v_add_f32_e32 v174, v174, v175
	v_add_f32_e32 v164, v164, v174
	s_waitcnt vmcnt(0)
	ds_write_b128 v218, v[144:147]
	ds_write_b128 v219, v[148:151]
	s_cmp_ge_u32 s34, s35
	s_cbranch_scc1 .Lattn_kskip_s
	v_lshl_add_u64 v[170:171], v[166:167], 0, s[22:23]
	v_add_co_u32_e32 v172, vcc, 0xc5c8000, v170
	s_nop 1
	v_addc_co_u32_e32 v173, vcc, 0, v171, vcc
	v_add_co_u32_e32 v170, vcc, 0xc5d8000, v170
	s_nop 1
	v_addc_co_u32_e32 v171, vcc, 0, v171, vcc
	global_load_dwordx4 v[144:147], v[172:173], off
	global_load_dwordx4 v[148:151], v[170:171], off
; #define LAS __attribute__((address_space(3)))
; #define SB0() __builtin_amdgcn_sched_barrier(0)
; template <bool SHIFT> DI void attn_unit(LAS unsigned char* lds, const bf16_t* Qb, const bf16_t* Kb, const bf16_t* Vt, bf16_t* concat,
;                   int b, int h, int qt, float shift2, float lam, int lam_init_bits, const float* subln_g) {
;     ...
;         if (pf) { *(LAS u32x4*)(lds + K_OFF + nx * K_BYTES + krow0 * QP + kc * 16) = sg0; *(LAS u32x4*)(lds + K_OFF + nx * K_BYTES + (krow0 + 32) * QP + kc * 16) = sg1;
;             sg0 = *(const u32x4*)(vg + (size_t)(vrow0) * TPB + ko + vc * 8); sg1 = *(const u32x4*)(vg + (size_t)(vrow0 + 64) * TPB + ko + vc * 8); }
;         const LAS unsigned char* kb = lds + K_OFF + cur * K_BYTES + r * QP + hh * 16;
;         const LAS unsigned char* vb = lds + V_OFF + vcur * V_BYTES + r * VP + hh * 16;
; #pragma unroll
;         for (int half = 0; half < 2; ++half) {
;             if (lag) PVH(Pc, vold);
;             QKEXP(Pc, half);
;             if (half == 0 && pf) { *(LAS u32x4*)(lds + V_OFF + vnx * V_BYTES + vrow0 * VP + vc * 16) = sg0; *(LAS u32x4*)(lds + V_OFF + vnx * V_BYTES + (vrow0 + 64) * VP + vc * 16) = sg1;
;                 if (kt + 2 < nkt) { sg0 = *(const u32x4*)(kg + (ko + 64 + krow0) * 1024 + kc * 8); sg1 = *(const u32x4*)(kg + (ko + 64 + krow0 + 32) * 1024 + kc * 8); } }
;             vold = vb + half * 64;
;             SB0();
;             if (!lag) PVH(Pc, vold);
;         }
;         __syncthreads();
;         vcur = vnx;
.Lattn_kskip_s:
	v_mfma_f32_32x32x16_bf16 v[238:253], v[178:181], v[186:189], 0
	ds_read_b128 v[178:181], v254 offset:8768
	ds_read_b128 v[186:189], v211 offset:64
	v_mfma_f32_32x32x16_bf16 v[238:253], v[182:185], v[190:193], v[238:253]
	ds_read_b128 v[182:185], v254 offset:8800
	ds_read_b128 v[190:193], v211 offset:96
	s_waitcnt lgkmcnt(2)
	v_mfma_f32_32x32x16_bf16 v[238:253], v[178:181], v[186:189], v[238:253]
	ds_read_b128 v[228:231], v217
	ds_read_b128 v[178:181], v254 offset:8832
	ds_read_b128 v[186:189], v211 offset:128
	s_waitcnt lgkmcnt(3)
	v_mfma_f32_32x32x16_bf16 v[238:253], v[182:185], v[190:193], v[238:253]
	ds_read_b128 v[232:235], v217 offset:4608
	ds_read_b128 v[182:185], v254 offset:8864
	ds_read_b128 v[190:193], v211 offset:160
	s_waitcnt lgkmcnt(5)
	v_mfma_f32_32x32x16_bf16 v[112:127], v[228:231], v[194:197], v[112:127]
	v_mfma_f32_32x32x16_bf16 v[96:111], v[228:231], v[202:205], v[96:111]
	ds_read_b128 v[228:231], v217 offset:9216
	s_nop 7
	s_waitcnt lgkmcnt(3)
	v_mfma_f32_32x32x16_bf16 v[80:95], v[232:235], v[194:197], v[80:95]
	v_exp_f32_e32 v238, v238
	v_exp_f32_e32 v239, v239
	v_exp_f32_e32 v240, v240
	v_exp_f32_e32 v241, v241
	v_add_f32_e32 v174, v238, v239
	v_add_f32_e32 v175, v240, v241
	v_cvt_pk_bf16_f32 v156, v238, v239
	v_mfma_f32_32x32x16_bf16 v[64:79], v[232:235], v[202:205], v[64:79]
	ds_read_b128 v[232:235], v217 offset:13824
	v_cvt_pk_bf16_f32 v157, v240, v241
	v_exp_f32_e32 v242, v242
	v_exp_f32_e32 v243, v243
	v_exp_f32_e32 v244, v244
	v_exp_f32_e32 v245, v245
	v_add_f32_e32 v174, v174, v242
	v_add_f32_e32 v175, v175, v243
	s_waitcnt lgkmcnt(1)
	v_mfma_f32_32x32x16_bf16 v[32:47], v[228:231], v[194:197], v[32:47]
	v_add_f32_e32 v174, v174, v244
	v_add_f32_e32 v175, v175, v245
	v_cvt_pk_bf16_f32 v158, v242, v243
	v_cvt_pk_bf16_f32 v159, v244, v245
	v_exp_f32_e32 v246, v246
	v_exp_f32_e32 v247, v247
	v_exp_f32_e32 v248, v248
	v_mfma_f32_32x32x16_bf16 v[48:63], v[228:231], v[202:205], v[48:63]
	ds_read_b128 v[228:231], v217 offset:32
	v_exp_f32_e32 v249, v249
	v_add_f32_e32 v174, v174, v246
	v_add_f32_e32 v175, v175, v247
	v_add_f32_e32 v174, v174, v248
	v_add_f32_e32 v175, v175, v249
	v_cvt_pk_bf16_f32 v152, v246, v247
	v_cvt_pk_bf16_f32 v153, v248, v249
	s_waitcnt lgkmcnt(1)
	v_mfma_f32_32x32x16_bf16 v[16:31], v[232:235], v[194:197], v[16:31]
	v_exp_f32_e32 v250, v250
	v_exp_f32_e32 v251, v251
	v_exp_f32_e32 v252, v252
	v_exp_f32_e32 v253, v253
	v_add_f32_e32 v174, v174, v250
	v_add_f32_e32 v175, v175, v251
	v_mfma_f32_32x32x16_bf16 v[0:15], v[232:235], v[202:205], v[0:15]
	ds_read_b128 v[232:235], v217 offset:4640
	v_add_f32_e32 v174, v174, v252
	v_add_f32_e32 v175, v175, v253
	v_cvt_pk_bf16_f32 v154, v250, v251
	v_cvt_pk_bf16_f32 v155, v252, v253
	v_add_f32_e32 v174, v174, v175
	v_add_f32_e32 v165, v165, v174
	v_mfma_f32_32x32x16_bf16 v[238:253], v[178:181], v[186:189], 0
	ds_read_b128 v[178:181], v254 offset:8896
	ds_read_b128 v[186:189], v211 offset:192
	v_mfma_f32_32x32x16_bf16 v[238:253], v[182:185], v[190:193], v[238:253]
	ds_read_b128 v[182:185], v254 offset:8928
	ds_read_b128 v[190:193], v211 offset:224
	s_waitcnt lgkmcnt(2)
	v_mfma_f32_32x32x16_bf16 v[238:253], v[178:181], v[186:189], v[238:253]
	s_waitcnt lgkmcnt(0)
	v_mfma_f32_32x32x16_bf16 v[238:253], v[182:185], v[190:193], v[238:253]
	v_mfma_f32_32x32x16_bf16 v[112:127], v[228:231], v[198:201], v[112:127]
	v_mfma_f32_32x32x16_bf16 v[96:111], v[228:231], v[206:209], v[96:111]
	ds_read_b128 v[228:231], v217 offset:9248
	s_nop 7
	v_mfma_f32_32x32x16_bf16 v[80:95], v[232:235], v[198:201], v[80:95]
	v_exp_f32_e32 v238, v238
	v_exp_f32_e32 v239, v239
	v_exp_f32_e32 v240, v240
	v_exp_f32_e32 v241, v241
	v_add_f32_e32 v174, v238, v239
	v_add_f32_e32 v175, v240, v241
	v_cvt_pk_bf16_f32 v132, v238, v239
	v_mfma_f32_32x32x16_bf16 v[64:79], v[232:235], v[206:209], v[64:79]
	ds_read_b128 v[232:235], v217 offset:13856
	v_cvt_pk_bf16_f32 v133, v240, v241
	v_exp_f32_e32 v242, v242
	v_exp_f32_e32 v243, v243
	v_exp_f32_e32 v244, v244
	v_exp_f32_e32 v245, v245
	v_add_f32_e32 v174, v174, v242
	v_add_f32_e32 v175, v175, v243
	s_waitcnt lgkmcnt(1)
	v_mfma_f32_32x32x16_bf16 v[32:47], v[228:231], v[198:201], v[32:47]
	v_add_f32_e32 v174, v174, v244
	v_add_f32_e32 v175, v175, v245
	v_cvt_pk_bf16_f32 v134, v242, v243
	v_cvt_pk_bf16_f32 v135, v244, v245
	v_exp_f32_e32 v246, v246
	v_exp_f32_e32 v247, v247
	v_exp_f32_e32 v248, v248
	v_mfma_f32_32x32x16_bf16 v[48:63], v[228:231], v[206:209], v[48:63]
	v_exp_f32_e32 v249, v249
	v_add_f32_e32 v174, v174, v246
	v_add_f32_e32 v175, v175, v247
	v_add_f32_e32 v174, v174, v248
	v_add_f32_e32 v175, v175, v249
	v_cvt_pk_bf16_f32 v128, v246, v247
	v_cvt_pk_bf16_f32 v129, v248, v249
	s_waitcnt lgkmcnt(0)
	v_mfma_f32_32x32x16_bf16 v[16:31], v[232:235], v[198:201], v[16:31]
	v_exp_f32_e32 v250, v250
	v_exp_f32_e32 v251, v251
	v_exp_f32_e32 v252, v252
	v_exp_f32_e32 v253, v253
	v_add_f32_e32 v174, v174, v250
	v_add_f32_e32 v175, v175, v251
	v_mfma_f32_32x32x16_bf16 v[0:15], v[232:235], v[206:209], v[0:15]
	v_add_f32_e32 v174, v174, v252
	v_add_f32_e32 v175, v175, v253
	v_cvt_pk_bf16_f32 v130, v250, v251
	v_cvt_pk_bf16_f32 v131, v252, v253
	v_add_f32_e32 v174, v174, v175
	v_add_f32_e32 v164, v164, v174
	s_add_u32 s22, s22, 0x20000
	s_addc_u32 s23, s23, 0
	s_add_i32 s34, s34, 1
	v_add_u32_e32 v136, 64, v217
	v_lshl_add_u64 v[168:169], v[168:169], 0, s[56:57]
	s_and_b32 vcc_lo, s34, 1
	s_xor_b32 vcc_hi, vcc_lo, 1
	s_mulk_i32 vcc_hi, 0x4400
	s_add_i32 vcc_hi, vcc_hi, 0x11000
	v_add3_u32 v137, vcc_hi, v210, v160
	v_add3_u32 v142, vcc_hi, v214, v160
	s_mulk_i32 vcc_lo, 0x4400
	v_add_u32_e32 v254, vcc_lo, v212
	s_add_i32 vcc_lo, s65, 1
	s_cmp_lg_u32 s65, 2
	s_cselect_b32 vcc_lo, vcc_lo, 0
	s_mul_i32 vcc_lo, vcc_lo, 0x4800
	s_add_i32 vcc_lo, vcc_lo, 0x19800
	v_add3_u32 v218, vcc_lo, v215, v176
	v_add3_u32 v219, vcc_lo, v216, v176
	v_add_co_u32_e32 v138, vcc, 0xffef8000, v168
	s_nop 1
	v_addc_co_u32_e32 v139, vcc, -1, v169, vcc
	s_waitcnt lgkmcnt(0)
	s_cmp_eq_u32 s36, s22
	s_barrier
	s_cbranch_scc1 .LBB0_545
	s_mov_b32 s40, s65
	s_branch .Lattn_loop
